# E28b+gen3: MLA loop re-generated: running-max shift folded into the QK accumulator init (SrcC), exps in place, scale/shift VALU removed; exps/cvts re-placed beside the QK/PV MFMAs, V loads issued earl
# speedup vs baseline: 1.1595x; 1.0290x over previous
; DEVINL unsigned char* wsp(const Params& p) { unsigned char* w = p.ws; asm volatile("" : "+s"(w)); return w; }
; DEVINL void phase_attn(const Params& p, char* lds) {
;     ...
;   {
;     const bf16_t* QN = (const bf16_t*)(wsp(p) + OFF_QN); const bf16_t* QRp = (const bf16_t*)(wsp(p) + OFF_QR);
;     const char* K8 = (const char*)(wsp(p) + OFF_K8); const char* KP8 = (const char*)(wsp(p) + OFF_KP8); const char* V8 = (const char*)(wsp(p) + OFF_V);
;     const bf16_t* G = (const bf16_t*)p.out; bf16_t* YM = (bf16_t*)(wsp(p) + OFF_YM);
;     for (int it = blockIdx.x; it < 512; it += gridDim.x) {
;       const int h = it & 7, qb = it >> 3;
;       mla_block(p, QN + ((size_t)h * SEQ + qb * 256) * 128, QRp + ((size_t)h * SEQ + qb * 256) * 64, K8 + (size_t)h * (LP / 64) * 6144, KP8, V8 + (size_t)h * (LP / 64) * 8192,
;                 G + (size_t)qb * 256 * 1024 + h * 128, YM + (size_t)qb * 256 * 1024 + h * 128, lds, NMETA + qb * 256);
.LBB0_546:
	s_cmp_lt_i32 s76, 5
	s_cselect_b64 s[28:29], -1, 0
	s_and_b64 s[4:5], s[28:29], s[38:39]
	s_andn2_b64 vcc, exec, s[4:5]
	s_cbranch_vccnz .LBB0_620
	s_mov_b64 s[6:7], s[72:73]
	s_mov_b64 s[8:9], s[72:73]
	s_mov_b64 s[10:11], s[72:73]
	s_mov_b64 s[4:5], s[72:73]
	s_mov_b64 s[30:31], s[72:73]
	s_mov_b64 s[12:13], s[72:73]
	s_cmpk_gt_i32 s2, 0x1ff
	s_cbranch_scc1 .LBB0_583
	s_add_u32 s33, s6, 0xaa58400
	s_addc_u32 s51, s7, 0
	s_add_u32 s54, s8, 0xca58400
	s_addc_u32 s55, s9, 0
	s_add_u32 s56, s10, 0x9a18400
	s_addc_u32 s57, s11, 0
	s_add_u32 s34, s4, 0xfa58400
	s_addc_u32 s35, s5, 0
	s_add_u32 s58, s30, 0x89d8400
	s_addc_u32 s59, s31, 0
	s_add_u32 s62, s12, 0xda58400
	s_addc_u32 s63, s13, 0
	s_add_u32 s38, s4, 0xfa59000
	s_addc_u32 s39, s5, 0
	s_add_u32 s40, s4, 0xfa59c00
	s_addc_u32 s41, s5, 0
	s_add_u32 s42, s0, 0xa8
	s_addc_u32 s43, s1, 0
	s_mov_b32 s13, 0
	v_mov_b32_e32 v139, 0
	s_mov_b64 s[44:45], 0x1800
	s_mov_b64 s[46:47], 0x3000
	s_add_i32 s68, 0, 0x11000
	s_mov_b64 s[48:49], 0x2000
	v_mov_b32_e32 v162, 0x7f7f7f7f
	s_mov_b32 s69, 0x4100ca7a
	s_mov_b32 s50, 1.0
	v_mov_b32_e32 v143, 0x7c7c7c7c
	v_mov_b32_e32 v163, 0xf149f2ca
	v_mov_b32_e32 v164, 0x40400000
	v_mov_b32_e32 v112, 0x38383838
	s_mov_b32 s74, s2
	s_branch .LBB0_550

; #define SBAR() __builtin_amdgcn_sched_barrier(0)
; DEVINL i32x8 mk6(int a, int b, int c, int d, int e, int f) { i32x8 r = __builtin_nondeterministic_value(r); r[0] = a; r[1] = b; r[2] = c; r[3] = d; r[4] = e; r[5] = f; return r; }
; #define MFMA6(A, B, C) __builtin_amdgcn_mfma_scale_f32_32x32x64_f8f6f4(A, B, C, 2, 2, 0, 0x7f7f7f7f, 0, 0x7f7f7f7f)
; #define ISSUE_K(j) do { const int _t = (j) < NT ? (j) : NT - 1; char* _d = K_lds + ((j) & 3) * SHM_K8; if (wid < 6) GLDS(K8 + (size_t)_t * 6144 + t16u, _d + tid16); \
;     if (wid < 3) GLDS(Kp8 + (size_t)_t * 3072 + t16u, _d + 6144 + tid16); } while (0)
; #define TILE_SYNC() do { asm volatile("s_waitcnt vmcnt(0)" ::: "memory"); __syncthreads(); } while (0)
; template <bool FUSE>
; DEVINL void qkt(f32x16& p0, f32x16& p1, const char* Ks, const i32x8* q8, int r32, int hi, f32x16& e1) {
;   p0 = f32x16{}; p1 = f32x16{};
;   const char* ka = Ks + hi * 1024 + r32 * 16; const char* kb = Ks + 4096 + hi * 512 + r32 * 8;
;   const char* ra = Ks + 6144 + hi * 1024 + r32 * 16; const char* rb = Ks + 6144 + 2048 + hi * 512 + r32 * 8;
;   u32x4 fa[3][2]; u32x2 fb[3][2];
;     ...
;   QK_LD(0, 0);
; #pragma unroll
;   for (int t = 0; t < 3; ++t) {
;     if (t + 1 < 3) QK_LD(t + 1, (t + 1) % 3);
;     const i32x8 a0 = mk6((int)fa[t][0][0], (int)fa[t][0][1], (int)fa[t][0][2], (int)fa[t][0][3], (int)fb[t][0][0], (int)fb[t][0][1]);
;     const i32x8 a1 = mk6((int)fa[t][1][0], (int)fa[t][1][1], (int)fa[t][1][2], (int)fa[t][1][3], (int)fb[t][1][0], (int)fb[t][1][1]);
;     p0 = MFMA6(a0, q8[t], p0);
;     if (FUSE) {
; #pragma unroll
;       for (int r = 0; r < 3; ++r) { const int rr = t * 6 + r; if (rr < 16) e1[rr] = __builtin_amdgcn_exp2f(e1[rr]); }
;     }
;     p1 = MFMA6(a1, q8[t], p1);
;     if (FUSE) {
; #pragma unroll
;       for (int r = 3; r < 6; ++r) { const int rr = t * 6 + r; if (rr < 16) e1[rr] = __builtin_amdgcn_exp2f(e1[rr]); }
;     }
;     SBAR();
;   }
; DEVINL void mla_block(const Params& p, const bf16_t* __restrict__ Qn, const bf16_t* __restrict__ Qr, const char* __restrict__ K8, const char* __restrict__ Kp8,
;                       const char* __restrict__ V8, const bf16_t* __restrict__ Gb, bf16_t* __restrict__ Yb, char* lds, int pos0) {
;     ...
;   ISSUE_K(0); ISSUE_K(1); ISSUE_K(2); ISSUE_V(0); ISSUE_V(1); TILE_SYNC();
;   qkt<false>(pA0, pA1, KS(0), q8, r32, hi, pA1); partialSM(pA0, pA1, m_reg, mnA, alA, 64, hi);
.LBB0_559:
	s_or_b64 exec, exec, s[8:9]
	s_mul_i32 s8, s75, 0x208000
	s_add_u32 s14, s58, s8
	v_add_u32_e32 v0, 0x9000, v172
	s_addc_u32 s15, s59, 0
	v_readfirstlane_b32 s9, v0
	v_add_u32_e32 v2, 0xb000, v172
	v_lshl_add_u64 v[140:141], s[14:15], 0, v[138:139]
	s_mov_b32 m0, s9
	v_readfirstlane_b32 s9, v2
	global_load_lds_dwordx4 v[140:141], off
	v_lshl_add_u64 v[0:1], v[140:141], 0, s[48:49]
	s_mov_b32 m0, s9
	v_lshlrev_b32_e32 v170, 9, v48
	global_load_lds_dwordx4 v[0:1], off
	v_and_b32_e32 v0, 0x3fffffc0, v166
	v_lshl_add_u32 v171, v0, 2, s68
	v_add_u32_e32 v0, 0, v170
	v_lshlrev_b32_e32 v176, 3, v167
	v_lshlrev_b32_e32 v175, 4, v167
	v_add_u32_e32 v49, v0, v176
	v_add3_u32 v173, v0, v170, v175
	v_add_u32_e32 v0, 0x1000, v49
	s_waitcnt vmcnt(0)
	s_waitcnt vmcnt(0) lgkmcnt(0)
	s_barrier
	ds_read2_b64 v[4:7], v0 offset1:32
	ds_read_b128 v[50:53], v173 offset:2048
	ds_read_b128 v[56:59], v173 offset:2560
	ds_read2_b64 v[60:63], v0 offset0:128 offset1:160
	ds_read_b128 v[16:19], v173 offset:512
	ds_read_b128 v[0:3], v173
	s_waitcnt lgkmcnt(5)
	v_mov_b32_e32 v20, v6
	v_mov_b32_e32 v21, v7
	s_waitcnt lgkmcnt(0)
	v_mfma_scale_f32_32x32x64_f8f6f4 v[32:47], v[0:5], v[120:125], 0, v162, v143 op_sel_hi:[0,0,0] cbsz:2 blgp:2
	s_mov_b32 s12, s13
	s_mov_b32 s14, s13
	s_mov_b32 s15, s13
	s_mov_b32 s16, s13
	s_mov_b32 s17, s13
	s_mov_b32 s18, s13
	s_mov_b32 s19, s13
	v_mfma_scale_f32_32x32x64_f8f6f4 v[16:31], v[16:21], v[120:125], 0, v162, v143 op_sel_hi:[0,0,0] cbsz:2 blgp:2
	s_mov_b32 s20, s13
	s_mov_b32 s21, s13
	s_mov_b32 s22, s13
	s_mov_b32 s23, s13
	s_mov_b32 s24, s13
	s_mov_b32 s25, s13
	s_mov_b32 s26, s13
	s_mov_b32 s27, s13
	v_mov_b64_e32 v[0:1], s[12:13]
	v_and_b32_e32 v169, 63, v166
	v_lshlrev_b32_e32 v174, 10, v48
	s_mov_b32 s53, 4
	v_mov_b64_e32 v[2:3], s[14:15]
	v_mov_b64_e32 v[4:5], s[16:17]
	v_mov_b64_e32 v[6:7], s[18:19]
	v_mov_b64_e32 v[8:9], s[20:21]
	v_mov_b64_e32 v[10:11], s[22:23]
	v_mov_b64_e32 v[12:13], s[24:25]
	v_mov_b64_e32 v[14:15], s[26:27]
	v_mov_b32_e32 v54, v60
	v_mov_b32_e32 v55, v61
	v_mov_b32_e32 v60, v62
	v_mov_b32_e32 v61, v63
	v_add_u32_e32 v49, 0x2000, v49
	v_mfma_scale_f32_32x32x64_f8f6f4 v[32:47], v[50:55], v[126:131], v[32:47], v162, v143 op_sel_hi:[0,0,0] cbsz:2 blgp:2
	ds_read_b128 v[50:53], v173 offset:6144
	ds_read_b128 v[62:65], v173 offset:6656
	ds_read2_b64 v[66:69], v49 offset1:32
	v_mfma_scale_f32_32x32x64_f8f6f4 v[16:31], v[56:61], v[126:131], v[16:31], v162, v143 op_sel_hi:[0,0,0] cbsz:2 blgp:2
	s_waitcnt lgkmcnt(0)
; DEVINL int crow(int r, int hi) { return (r & 3) + 8 * (r >> 2) + 4 * hi; }
; #define SBAR() __builtin_amdgcn_sched_barrier(0)
; DEVINL void partialSM(f32x16& p0, f32x16& p1, float& m_reg, float& mn, float& alpha, int kvalid, int hi) {
;   constexpr float C = MLA_SCALE * 1.4426950408889634f;
;   if (kvalid < 64) {
; #pragma unroll
;     for (int r = 0; r < 16; ++r) { if (crow(r, hi) >= kvalid) p0[r] = -1e30f; if (32 + crow(r, hi) >= kvalid) p1[r] = -1e30f; }
;   }
;   float pmax = p0[0];
; #pragma unroll
;   for (int r = 1; r < 16; ++r) pmax = fmaxf(pmax, p0[r]);
; #pragma unroll
;   for (int r = 0; r < 16; ++r) pmax = fmaxf(pmax, p1[r]);
;   { auto rr = __builtin_amdgcn_permlane32_swap(__float_as_uint(pmax), __float_as_uint(pmax), false, false);
;     pmax = fmaxf(__uint_as_float(rr[0]), __uint_as_float(rr[1])); }
;   if (__builtin_expect(__all(pmax - m_reg <= THR / MLA_SCALE), 1)) { mn = m_reg; alpha = 1.f; }
;   else { mn = fmaxf(m_reg, pmax); alpha = __builtin_amdgcn_exp2f((m_reg - mn) * C); m_reg = mn; }
;   const float mnC = PSHIFT - mn * C;
;   const f32x2 C2 = {C, C}, M2 = {mnC, mnC};
; #pragma unroll
;   for (int r = 0; r < 16; r += 2) { f32x2 v = {p0[r], p0[r + 1]}; v = __builtin_elementwise_fma(v, C2, M2); p0[r] = v[0]; p0[r + 1] = v[1]; }
; #pragma unroll
;   for (int r = 0; r < 16; r += 2) { f32x2 v = {p1[r], p1[r + 1]}; v = __builtin_elementwise_fma(v, C2, M2); p1[r] = v[0]; p1[r + 1] = v[1]; }
; #pragma unroll
;   for (int r = 0; r < 16; ++r) p0[r] = __builtin_amdgcn_exp2f(p0[r]);
; DEVINL void mla_block(const Params& p, const bf16_t* __restrict__ Qn, const bf16_t* __restrict__ Qr, const char* __restrict__ K8, const char* __restrict__ Kp8,
;                       const char* __restrict__ V8, const bf16_t* __restrict__ Gb, bf16_t* __restrict__ Yb, char* lds, int pos0) {
;     ...
;   SBAR();
; #pragma unroll
;   for (int d = 0; d < 4; ++d) o[d] = f32x16{};
;   const int tid16 = tid * 16;
;   const unsigned t16u = (unsigned)tid16;
;     ...
;   f32x16 pA0, pA1, pB0, pB1; float mnA, mnB, alA, alB; i32x8 pa; VFrag vf; constexpr int NT = NT_MLA;
;   const i32x8 ones8 = {0x38383838, 0x38383838, 0x38383838, 0x38383838, 0x38383838, 0x38383838, 0x38383838, 0x38383838};
;   f32x16 lsum;
;     ...
;   ISSUE_K(0); ISSUE_K(1); ISSUE_K(2); ISSUE_V(0); ISSUE_V(1); TILE_SYNC();
;   qkt<false>(pA0, pA1, KS(0), q8, r32, hi, pA1); partialSM(pA0, pA1, m_reg, mnA, alA, 64, hi);
	v_mov_b32_e32 v54, v66
	v_mov_b32_e32 v55, v67
	v_mov_b32_e32 v66, v68
	v_mov_b32_e32 v67, v69
	v_mfma_scale_f32_32x32x64_f8f6f4 v[32:47], v[50:55], v[132:137], v[32:47], v162, v143 op_sel_hi:[0,0,0] cbsz:2 blgp:2
	s_nop 0
	v_mfma_scale_f32_32x32x64_f8f6f4 v[16:31], v[62:67], v[132:137], v[16:31], v162, v143 op_sel_hi:[0,0,0] cbsz:2 blgp:2
	s_nop 9
	v_max_f32_e32 v49, v33, v33
	v_max_f32_e32 v50, v32, v32
	v_max_f32_e32 v49, v50, v49
	v_max3_f32 v49, v49, v34, v35
	v_max3_f32 v49, v49, v36, v37
	v_max3_f32 v49, v49, v38, v39
	v_max3_f32 v49, v49, v40, v41
	v_max3_f32 v49, v49, v42, v43
	v_max3_f32 v49, v49, v44, v45
	v_max3_f32 v49, v49, v46, v47
	v_max3_f32 v49, v49, v16, v17
	v_max3_f32 v49, v49, v18, v19
	v_max3_f32 v49, v49, v20, v21
	v_max3_f32 v49, v49, v22, v23
	v_max3_f32 v49, v49, v24, v25
	v_max3_f32 v49, v49, v26, v27
	v_max3_f32 v49, v49, v28, v29
	v_max3_f32 v49, v49, v30, v31
	v_mov_b32_e32 v50, v49
	s_nop 1
	v_permlane32_swap_b32_e32 v49, v50
	v_max_f32_e32 v50, v50, v50
	v_max_f32_e32 v49, v49, v49
	v_max_f32_e32 v49, v49, v50
	v_add_f32_e32 v50, 0x7149f2ca, v49
	v_max_f32_e32 v49, 0xf149f2ca, v49
	v_sub_f32_e32 v51, 0xf149f2ca, v49
	v_mul_f32_e32 v51, 1.0, v51
	v_cmp_ge_f32_e32 vcc, s69, v50
	v_exp_f32_e32 v51, v51
	s_cmp_eq_u64 vcc, exec
	s_cselect_b64 vcc, -1, 0
	v_cndmask_b32_e32 v181, v49, v163, vcc
	v_fmamk_f32 v50, v181, 0xbf800000, v164
	v_pk_fma_f32 v[32:33], v[32:33], s[50:51], v[50:51] op_sel_hi:[1,0,0]
	v_pk_fma_f32 v[34:35], v[34:35], s[50:51], v[50:51] op_sel_hi:[1,0,0]
	v_pk_fma_f32 v[36:37], v[36:37], s[50:51], v[50:51] op_sel_hi:[1,0,0]
	v_pk_fma_f32 v[38:39], v[38:39], s[50:51], v[50:51] op_sel_hi:[1,0,0]
	v_pk_fma_f32 v[40:41], v[40:41], s[50:51], v[50:51] op_sel_hi:[1,0,0]
	v_pk_fma_f32 v[42:43], v[42:43], s[50:51], v[50:51] op_sel_hi:[1,0,0]
	v_pk_fma_f32 v[44:45], v[44:45], s[50:51], v[50:51] op_sel_hi:[1,0,0]
	v_pk_fma_f32 v[46:47], v[46:47], s[50:51], v[50:51] op_sel_hi:[1,0,0]
	v_exp_f32_e32 v65, v32
	v_exp_f32_e32 v197, v33
	v_exp_f32_e32 v187, v34
	v_exp_f32_e32 v189, v35
	v_exp_f32_e32 v195, v36
	v_exp_f32_e32 v196, v37
	v_exp_f32_e32 v191, v38
	v_exp_f32_e32 v192, v39
	v_exp_f32_e32 v193, v40
	v_exp_f32_e32 v194, v41
	v_exp_f32_e32 v183, v42
	v_exp_f32_e32 v184, v43
	v_exp_f32_e32 v188, v44
	v_exp_f32_e32 v190, v45
	v_exp_f32_e32 v185, v46
	v_exp_f32_e32 v186, v47
	s_add_u32 s8, s30, s8
	v_cndmask_b32_e64 v179, v51, 1.0, vcc
	v_pk_fma_f32 v[148:149], v[30:31], s[50:51], v[50:51] op_sel_hi:[1,0,0]
	v_pk_fma_f32 v[150:151], v[28:29], s[50:51], v[50:51] op_sel_hi:[1,0,0]
	v_pk_fma_f32 v[152:153], v[26:27], s[50:51], v[50:51] op_sel_hi:[1,0,0]
	v_pk_fma_f32 v[154:155], v[24:25], s[50:51], v[50:51] op_sel_hi:[1,0,0]
	v_pk_fma_f32 v[156:157], v[22:23], s[50:51], v[50:51] op_sel_hi:[1,0,0]
	v_pk_fma_f32 v[82:83], v[20:21], s[50:51], v[50:51] op_sel_hi:[1,0,0]
	v_pk_fma_f32 v[158:159], v[18:19], s[50:51], v[50:51] op_sel_hi:[1,0,0]
	v_pk_fma_f32 v[160:161], v[16:17], s[50:51], v[50:51] op_sel_hi:[1,0,0]
	v_lshlrev_b32_e32 v177, 4, v48
	s_addc_u32 s9, s31, 0
	v_mov_b64_e32 v[62:63], v[14:15]
	v_mov_b64_e32 v[30:31], v[14:15]
	v_mov_b64_e32 v[46:47], v[14:15]
	v_lshl_add_u64 v[144:145], s[34:35], 0, v[138:139]
	v_cmp_gt_u32_e64 s[6:7], 32, v169
	v_lshl_add_u32 v178, v167, 2, v171
	v_lshl_add_u64 v[146:147], s[8:9], 0, v[138:139]
	v_mov_b32_e32 v180, 0
	s_mov_b64 s[14:15], 0x89dc400
	v_mov_b64_e32 v[60:61], v[12:13]
	v_mov_b64_e32 v[58:59], v[10:11]
	v_mov_b64_e32 v[56:57], v[8:9]
	v_mov_b64_e32 v[54:55], v[6:7]
	v_mov_b64_e32 v[52:53], v[4:5]
	v_mov_b64_e32 v[50:51], v[2:3]
	v_mov_b64_e32 v[48:49], v[0:1]
	v_mov_b64_e32 v[28:29], v[12:13]
	v_mov_b64_e32 v[26:27], v[10:11]
	v_mov_b64_e32 v[24:25], v[8:9]
	v_mov_b64_e32 v[22:23], v[6:7]
	v_mov_b64_e32 v[20:21], v[4:5]
	v_mov_b64_e32 v[18:19], v[2:3]
	v_mov_b64_e32 v[16:17], v[0:1]
	v_mov_b64_e32 v[44:45], v[12:13]
	v_mov_b64_e32 v[42:43], v[10:11]
	v_mov_b64_e32 v[40:41], v[8:9]
	v_mov_b64_e32 v[38:39], v[6:7]
	v_mov_b64_e32 v[36:37], v[4:5]
	v_mov_b64_e32 v[34:35], v[2:3]
	v_mov_b64_e32 v[32:33], v[0:1]
	v_lshrrev_b32_e32 v175, 4, v169
	v_and_b32_e32 v175, 1, v175
	v_bfe_u32 v174, v169, 2, 2
	v_cmp_eq_u32_e64 s[8:9], v174, v175
	v_mov_b32_e32 v174, 0x38383838
	s_nop 1
	v_cndmask_b32_e64 v232, 0, v174, s[8:9]
	v_mov_b32_e32 v233, v232
	v_mov_b32_e32 v234, v232
	v_mov_b32_e32 v235, v232
	v_mov_b32_e32 v236, v232
	v_mov_b32_e32 v237, v232
	v_mov_b32_e32 v238, v232
	v_mov_b32_e32 v239, v232
	v_add_u32_e32 v176, v170, v176
	v_add_u32_e32 v176, 0x1000, v176
	v_mov_b32_e32 v64, v65
	v_mov_b32_e32 v84, v82
	v_mov_b32_e32 v85, v83
	v_mov_b32_e32 v65, v197
	v_mov_b32_e32 v66, v187
	v_mov_b32_e32 v67, v189
	v_mov_b32_e32 v68, v195
	v_mov_b32_e32 v69, v196
	v_mov_b32_e32 v70, v191
	v_mov_b32_e32 v71, v192
	v_mov_b32_e32 v72, v193
	v_mov_b32_e32 v73, v194
	v_mov_b32_e32 v74, v183
	v_mov_b32_e32 v75, v184
	v_mov_b32_e32 v76, v188
	v_mov_b32_e32 v77, v190
	v_mov_b32_e32 v78, v185
	v_mov_b32_e32 v79, v186
	v_mov_b32_e32 v80, v160
	v_mov_b32_e32 v81, v161
	v_mov_b32_e32 v82, v158
	v_mov_b32_e32 v83, v159
	v_mov_b32_e32 v86, v156
	v_mov_b32_e32 v87, v157
	v_mov_b32_e32 v88, v154
	v_mov_b32_e32 v89, v155
	v_mov_b32_e32 v90, v152
	v_mov_b32_e32 v91, v153
	v_mov_b32_e32 v92, v150
	v_mov_b32_e32 v93, v151
	v_mov_b32_e32 v94, v148
	v_mov_b32_e32 v95, v149
	s_lshl_b32 s78, s3, 4
	s_add_i32 s79, s78, 0x9000
	s_mul_i32 s80, s75, 0x186000
	s_add_u32 s80, s56, s80
	s_addc_u32 s81, s57, 0
	s_mov_b64 s[82:83], s[34:35]
	s_mul_i32 s84, s75, 0x208000
	s_add_u32 s84, s58, s84
	s_addc_u32 s85, s59, 0
	v_lshlrev_b32_e32 v231, 4, v169
	v_fmamk_f32 v230, v181, 0xbf800000, v164
	v_add_u32_e32 v140, 0x8000, v173
	v_mov_b32_e32 v240, v230
	v_mov_b32_e32 v241, v230
	v_mov_b32_e32 v242, v230
	v_mov_b32_e32 v243, v230
	v_mov_b32_e32 v244, v230
	v_mov_b32_e32 v245, v230
	v_mov_b32_e32 v246, v230
	v_mov_b32_e32 v247, v230
	v_mov_b32_e32 v248, v230
	v_mov_b32_e32 v249, v230
	v_mov_b32_e32 v250, v230
	v_mov_b32_e32 v251, v230
	v_mov_b32_e32 v252, v230
	v_mov_b32_e32 v253, v230
	v_mov_b32_e32 v254, v230
	v_mov_b32_e32 v255, v230
	ds_read_b128 v[104:107], v173 offset:9216
	ds_read_b64 v[108:109], v176 offset:9216
	ds_read_b128 v[110:113], v173 offset:9728
	ds_read_b64 v[114:115], v176 offset:9472
	ds_read_b128 v[148:151], v173 offset:11264
	ds_read_b64 v[152:153], v176 offset:10240
	ds_read_b128 v[154:157], v173 offset:11776
	ds_read_b64 v[158:159], v176 offset:10496
	ds_read_b128 v[214:217], v173 offset:15360
	ds_read_b64 v[218:219], v176 offset:13312
	ds_read_b128 v[220:223], v173 offset:15872
	ds_read_b64 v[224:225], v176 offset:13568
	s_cmp_ge_u32 s3, 0x100
	s_cbranch_scc1 .Lprio_skip
	s_setprio 2

; template <bool FUSE>
; DEVINL void qkt(f32x16& p0, f32x16& p1, const char* Ks, const i32x8* q8, int r32, int hi, f32x16& e1) {
;   p0 = f32x16{}; p1 = f32x16{};
;   const char* ka = Ks + hi * 1024 + r32 * 16; const char* kb = Ks + 4096 + hi * 512 + r32 * 8;
;   const char* ra = Ks + 6144 + hi * 1024 + r32 * 16; const char* rb = Ks + 6144 + 2048 + hi * 512 + r32 * 8;
;   u32x4 fa[3][2]; u32x2 fb[3][2];
;     ...
;   QK_LD(0, 0);
; #pragma unroll
;   for (int t = 0; t < 3; ++t) {
;     if (t + 1 < 3) QK_LD(t + 1, (t + 1) % 3);
;     const i32x8 a0 = mk6((int)fa[t][0][0], (int)fa[t][0][1], (int)fa[t][0][2], (int)fa[t][0][3], (int)fb[t][0][0], (int)fb[t][0][1]);
;     const i32x8 a1 = mk6((int)fa[t][1][0], (int)fa[t][1][1], (int)fa[t][1][2], (int)fa[t][1][3], (int)fb[t][1][0], (int)fb[t][1][1]);
;     p0 = MFMA6(a0, q8[t], p0);
;     if (FUSE) {
; #pragma unroll
;       for (int r = 0; r < 3; ++r) { const int rr = t * 6 + r; if (rr < 16) e1[rr] = __builtin_amdgcn_exp2f(e1[rr]); }
;     }
;     p1 = MFMA6(a1, q8[t], p1);
;     if (FUSE) {
; #pragma unroll
;       for (int r = 3; r < 6; ++r) { const int rr = t * 6 + r; if (rr < 16) e1[rr] = __builtin_amdgcn_exp2f(e1[rr]); }
;     }
;     SBAR();
;   }
; DEVINL void pv_psm(f32x16* o, const VFrag& f, const i32x8& pa, f32x16& lsum, const i32x8& ones8,
;                    f32x16& p0, f32x16& p1, float& m_reg, float& mn, float& alpha, int kvalid, int hi) {
;   constexpr float C = MLA_SCALE * 1.4426950408889634f;
;     ...
;   if (kvalid < 64) {
; #pragma unroll
;     for (int r = 0; r < 16; ++r) { if (crow(r, hi) >= kvalid) p0[r] = -1e30f; if (32 + crow(r, hi) >= kvalid) p1[r] = -1e30f; }
;   }
;   PVM(0);
;   float pmax = p0[0];
; #pragma unroll
;   for (int r = 1; r < 16; ++r) pmax = fmaxf(pmax, p0[r]);
;   SBAR();
;   PVM(1);
; #pragma unroll
;   for (int r = 0; r < 16; ++r) pmax = fmaxf(pmax, p1[r]);
;   { auto rr = __builtin_amdgcn_permlane32_swap(__float_as_uint(pmax), __float_as_uint(pmax), false, false);
;     pmax = fmaxf(__uint_as_float(rr[0]), __uint_as_float(rr[1])); }
;   SBAR();
;   PVM(2);
;   if (__builtin_expect(__all(pmax - m_reg <= THR / MLA_SCALE), 1)) { mn = m_reg; alpha = 1.f; }
;   else { mn = fmaxf(m_reg, pmax); alpha = __builtin_amdgcn_exp2f((m_reg - mn) * C); m_reg = mn; }
;   const float mnC = PSHIFT - mn * C;
;   const f32x2 C2 = {C, C}, M2 = {mnC, mnC};
; #pragma unroll
.Ldma_done:
	v_exp_f32_e32 v80, v80
	v_exp_f32_e32 v81, v81
	s_waitcnt lgkmcnt(10)
	v_mfma_scale_f32_32x32x64_f8f6f4 v[182:197], v[104:109], v[120:125], v[240:255], v162, v143 op_sel_hi:[0,0,0] cbsz:2 blgp:2
	v_exp_f32_e32 v82, v82
	v_exp_f32_e32 v83, v83
	v_exp_f32_e32 v84, v84
	v_exp_f32_e32 v85, v85
	s_waitcnt lgkmcnt(8)
	v_mfma_scale_f32_32x32x64_f8f6f4 v[198:213], v[110:115], v[120:125], v[240:255], v162, v143 op_sel_hi:[0,0,0] cbsz:2 blgp:2
	ds_read_b128 v[104:107], v140 offset:4096
	ds_read_b128 v[108:111], v140 offset:4608
	ds_read_b128 v[112:115], v140 offset:6144
	ds_read_b128 v[116:119], v140 offset:6656
	s_waitcnt lgkmcnt(10)
	v_exp_f32_e32 v86, v86
	v_mfma_scale_f32_32x32x64_f8f6f4 v[182:197], v[148:153], v[126:131], v[182:197], v162, v143 op_sel_hi:[0,0,0] cbsz:2 blgp:2
	v_exp_f32_e32 v87, v87
	v_exp_f32_e32 v88, v88
	v_exp_f32_e32 v89, v89
	v_exp_f32_e32 v90, v90
	s_waitcnt lgkmcnt(8)
	v_mfma_scale_f32_32x32x64_f8f6f4 v[198:213], v[154:159], v[126:131], v[198:213], v162, v143 op_sel_hi:[0,0,0] cbsz:2 blgp:2
	ds_read_b128 v[148:151], v140 offset:8192
	ds_read_b128 v[152:155], v140 offset:8704
	v_exp_f32_e32 v91, v91
	s_waitcnt lgkmcnt(8)
	v_exp_f32_e32 v92, v92
	v_mfma_scale_f32_32x32x64_f8f6f4 v[182:197], v[214:219], v[132:137], v[182:197], v162, v143 op_sel_hi:[0,0,0] cbsz:2 blgp:2
	v_exp_f32_e32 v93, v93
	v_exp_f32_e32 v94, v94
	v_exp_f32_e32 v95, v95
	v_cvt_pk_fp8_f32 v96, v64, v65
	v_cvt_pk_fp8_f32 v97, v68, v69
	s_waitcnt lgkmcnt(6)
	v_mfma_scale_f32_32x32x64_f8f6f4 v[198:213], v[220:225], v[132:137], v[198:213], v162, v143 op_sel_hi:[0,0,0] cbsz:2 blgp:2
	ds_read_b128 v[214:217], v140 offset:10240
	ds_read_b128 v[218:221], v140 offset:10752
	v_cvt_pk_fp8_f32 v98, v72, v73
	v_cvt_pk_fp8_f32 v99, v76, v77
	v_cvt_pk_fp8_f32 v96, v66, v67 op_sel:[0,0,1]
	v_cvt_pk_fp8_f32 v97, v70, v71 op_sel:[0,0,1]
	v_cvt_pk_fp8_f32 v98, v74, v75 op_sel:[0,0,1]
	v_cvt_pk_fp8_f32 v99, v78, v79 op_sel:[0,0,1]
	v_cvt_pk_fp8_f32 v100, v80, v81
	v_cvt_pk_fp8_f32 v101, v84, v85
	v_cvt_pk_fp8_f32 v102, v88, v89
	v_cvt_pk_fp8_f32 v103, v92, v93
	v_cvt_pk_fp8_f32 v100, v82, v83 op_sel:[0,0,1]
	v_cvt_pk_fp8_f32 v101, v86, v87 op_sel:[0,0,1]
	v_cvt_pk_fp8_f32 v102, v90, v91 op_sel:[0,0,1]
	v_cvt_pk_fp8_f32 v103, v94, v95 op_sel:[0,0,1]
	s_waitcnt lgkmcnt(6)
	s_nop 0
	v_mfma_scale_f32_32x32x64_f8f6f4 v[0:15], v[96:103], v[104:111], v[0:15], v162, v162 op_sel_hi:[0,0,0]
	v_max_f32_e32 v229, v182, v183
	v_max3_f32 v229, v229, v184, v185
	v_max3_f32 v229, v229, v186, v187
	v_max3_f32 v229, v229, v188, v189
	v_max3_f32 v229, v229, v190, v191
	v_max3_f32 v229, v229, v192, v193
	v_max3_f32 v229, v229, v194, v195
	v_max3_f32 v229, v229, v196, v197
	s_waitcnt lgkmcnt(4)
	v_mfma_scale_f32_32x32x64_f8f6f4 v[48:63], v[96:103], v[112:119], v[48:63], v162, v162 op_sel_hi:[0,0,0]
	v_max3_f32 v229, v229, v198, v199
	v_max3_f32 v229, v229, v200, v201
	v_max3_f32 v229, v229, v202, v203
	v_max3_f32 v229, v229, v204, v205
	v_max3_f32 v229, v229, v206, v207
	v_max3_f32 v229, v229, v208, v209
	v_max3_f32 v229, v229, v210, v211
	v_max3_f32 v229, v229, v212, v213
	v_mov_b32_e32 v160, v229
	s_nop 1
	v_permlane32_swap_b32_e32 v229, v160
	v_max_f32_e32 v229, v229, v160
	v_cmp_ge_f32_e32 vcc, s69, v229
	s_cmp_eq_u64 vcc, exec
	v_mov_b32_e32 v226, 1.0
	s_cbranch_scc0 .Lslow_a0
	s_waitcnt lgkmcnt(2)
	v_mfma_scale_f32_32x32x64_f8f6f4 v[16:31], v[96:103], v[148:155], v[16:31], v162, v162 op_sel_hi:[0,0,0]
	v_exp_f32_e32 v182, v182
	v_exp_f32_e32 v183, v183
	v_exp_f32_e32 v184, v184
	v_exp_f32_e32 v185, v185
	v_exp_f32_e32 v186, v186
	v_exp_f32_e32 v187, v187
	s_waitcnt lgkmcnt(0)
	v_mfma_scale_f32_32x32x64_f8f6f4 v[32:47], v[96:103], v[214:221], v[32:47], v162, v162 op_sel_hi:[0,0,0]
	v_exp_f32_e32 v188, v188
	v_exp_f32_e32 v189, v189
	v_exp_f32_e32 v190, v190
	v_exp_f32_e32 v191, v191
	v_exp_f32_e32 v192, v192
	v_exp_f32_e32 v193, v193
	v_mfma_scale_f32_16x16x128_f8f6f4 v[144:147], v[232:239], v[96:103], 0, v162, v162 op_sel_hi:[0,0,0]
	v_exp_f32_e32 v194, v194
	v_exp_f32_e32 v195, v195
	v_exp_f32_e32 v196, v196
	v_exp_f32_e32 v197, v197
; template <bool FUSE>
; DEVINL void qkt(f32x16& p0, f32x16& p1, const char* Ks, const i32x8* q8, int r32, int hi, f32x16& e1) {
;   p0 = f32x16{}; p1 = f32x16{};
;   const char* ka = Ks + hi * 1024 + r32 * 16; const char* kb = Ks + 4096 + hi * 512 + r32 * 8;
;   const char* ra = Ks + 6144 + hi * 1024 + r32 * 16; const char* rb = Ks + 6144 + 2048 + hi * 512 + r32 * 8;
;   u32x4 fa[3][2]; u32x2 fb[3][2];
;     ...
;   QK_LD(0, 0);
; #pragma unroll
;   for (int t = 0; t < 3; ++t) {
;     if (t + 1 < 3) QK_LD(t + 1, (t + 1) % 3);
;     const i32x8 a0 = mk6((int)fa[t][0][0], (int)fa[t][0][1], (int)fa[t][0][2], (int)fa[t][0][3], (int)fb[t][0][0], (int)fb[t][0][1]);
;     const i32x8 a1 = mk6((int)fa[t][1][0], (int)fa[t][1][1], (int)fa[t][1][2], (int)fa[t][1][3], (int)fb[t][1][0], (int)fb[t][1][1]);
;     p0 = MFMA6(a0, q8[t], p0);
;     if (FUSE) {
; #pragma unroll
;       for (int r = 0; r < 3; ++r) { const int rr = t * 6 + r; if (rr < 16) e1[rr] = __builtin_amdgcn_exp2f(e1[rr]); }
;     }
;     p1 = MFMA6(a1, q8[t], p1);
;     if (FUSE) {
; #pragma unroll
;       for (int r = 3; r < 6; ++r) { const int rr = t * 6 + r; if (rr < 16) e1[rr] = __builtin_amdgcn_exp2f(e1[rr]); }
;     }
;     SBAR();
;   }
; DEVINL void pv_psm(f32x16* o, const VFrag& f, const i32x8& pa, f32x16& lsum, const i32x8& ones8,
;                    f32x16& p0, f32x16& p1, float& m_reg, float& mn, float& alpha, int kvalid, int hi) {
;   constexpr float C = MLA_SCALE * 1.4426950408889634f;
;     ...
;   if (kvalid < 64) {
; #pragma unroll
;     for (int r = 0; r < 16; ++r) { if (crow(r, hi) >= kvalid) p0[r] = -1e30f; if (32 + crow(r, hi) >= kvalid) p1[r] = -1e30f; }
;   }
;   PVM(0);
;   float pmax = p0[0];
; #pragma unroll
;   for (int r = 1; r < 16; ++r) pmax = fmaxf(pmax, p0[r]);
;   SBAR();
;   PVM(1);
; #pragma unroll
;   for (int r = 0; r < 16; ++r) pmax = fmaxf(pmax, p1[r]);
;   { auto rr = __builtin_amdgcn_permlane32_swap(__float_as_uint(pmax), __float_as_uint(pmax), false, false);
;     pmax = fmaxf(__uint_as_float(rr[0]), __uint_as_float(rr[1])); }
;   SBAR();
;   PVM(2);
;   if (__builtin_expect(__all(pmax - m_reg <= THR / MLA_SCALE), 1)) { mn = m_reg; alpha = 1.f; }
;   else { mn = fmaxf(m_reg, pmax); alpha = __builtin_amdgcn_exp2f((m_reg - mn) * C); m_reg = mn; }
;   const float mnC = PSHIFT - mn * C;
;   const f32x2 C2 = {C, C}, M2 = {mnC, mnC};
; #pragma unroll
.Ljoin_a0:
	ds_read_b128 v[104:107], v173 offset:18432
	ds_read_b64 v[108:109], v176 offset:18432
	ds_read_b128 v[110:113], v173 offset:18944
	ds_read_b64 v[114:115], v176 offset:18688
	ds_read_b128 v[148:151], v173 offset:20480
	ds_read_b64 v[152:153], v176 offset:19456
	ds_read_b128 v[154:157], v173 offset:20992
	ds_read_b64 v[158:159], v176 offset:19712
	ds_read_b128 v[214:217], v173 offset:24576
	ds_read_b64 v[218:219], v176 offset:22528
	ds_read_b128 v[220:223], v173 offset:25088
	ds_read_b64 v[224:225], v176 offset:22784
	v_fma_f32 v180, v179, v180, v144
	v_exp_f32_e32 v198, v198
	v_exp_f32_e32 v199, v199
	s_waitcnt lgkmcnt(10)
	v_mfma_scale_f32_32x32x64_f8f6f4 v[64:79], v[104:109], v[120:125], v[240:255], v162, v143 op_sel_hi:[0,0,0] cbsz:2 blgp:2
	v_exp_f32_e32 v200, v200
	v_exp_f32_e32 v201, v201
	v_exp_f32_e32 v202, v202
	v_exp_f32_e32 v203, v203
	s_waitcnt lgkmcnt(8)
	v_mfma_scale_f32_32x32x64_f8f6f4 v[80:95], v[110:115], v[120:125], v[240:255], v162, v143 op_sel_hi:[0,0,0] cbsz:2 blgp:2
	ds_read_b128 v[104:107], v140 offset:12288
	ds_read_b128 v[108:111], v140 offset:12800
	ds_read_b128 v[112:115], v140 offset:14336
	ds_read_b128 v[116:119], v140 offset:14848
	s_waitcnt lgkmcnt(10)
	v_exp_f32_e32 v204, v204
	v_mfma_scale_f32_32x32x64_f8f6f4 v[64:79], v[148:153], v[126:131], v[64:79], v162, v143 op_sel_hi:[0,0,0] cbsz:2 blgp:2
	v_exp_f32_e32 v205, v205
	v_exp_f32_e32 v206, v206
	v_exp_f32_e32 v207, v207
	v_exp_f32_e32 v208, v208
	s_waitcnt lgkmcnt(8)
	v_mfma_scale_f32_32x32x64_f8f6f4 v[80:95], v[154:159], v[126:131], v[80:95], v162, v143 op_sel_hi:[0,0,0] cbsz:2 blgp:2
	ds_read_b128 v[148:151], v140 offset:16384
	ds_read_b128 v[152:155], v140 offset:16896
	v_exp_f32_e32 v209, v209
	s_waitcnt lgkmcnt(8)
	v_exp_f32_e32 v210, v210
	v_mfma_scale_f32_32x32x64_f8f6f4 v[64:79], v[214:219], v[132:137], v[64:79], v162, v143 op_sel_hi:[0,0,0] cbsz:2 blgp:2
	v_exp_f32_e32 v211, v211
	v_exp_f32_e32 v212, v212
	v_exp_f32_e32 v213, v213
	v_cvt_pk_fp8_f32 v96, v182, v183
	v_cvt_pk_fp8_f32 v97, v186, v187
	s_waitcnt lgkmcnt(6)
	v_mfma_scale_f32_32x32x64_f8f6f4 v[80:95], v[220:225], v[132:137], v[80:95], v162, v143 op_sel_hi:[0,0,0] cbsz:2 blgp:2
	ds_read_b128 v[214:217], v140 offset:18432
	ds_read_b128 v[218:221], v140 offset:18944
	v_cvt_pk_fp8_f32 v98, v190, v191
	v_cvt_pk_fp8_f32 v99, v194, v195
	v_cvt_pk_fp8_f32 v96, v184, v185 op_sel:[0,0,1]
	v_cvt_pk_fp8_f32 v97, v188, v189 op_sel:[0,0,1]
	v_cvt_pk_fp8_f32 v98, v192, v193 op_sel:[0,0,1]
	v_cvt_pk_fp8_f32 v99, v196, v197 op_sel:[0,0,1]
	v_cvt_pk_fp8_f32 v100, v198, v199
	v_cvt_pk_fp8_f32 v101, v202, v203
	v_cvt_pk_fp8_f32 v102, v206, v207
	v_cvt_pk_fp8_f32 v103, v210, v211
	v_cvt_pk_fp8_f32 v100, v200, v201 op_sel:[0,0,1]
	v_cvt_pk_fp8_f32 v101, v204, v205 op_sel:[0,0,1]
	v_cvt_pk_fp8_f32 v102, v208, v209 op_sel:[0,0,1]
	v_cvt_pk_fp8_f32 v103, v212, v213 op_sel:[0,0,1]
	s_waitcnt lgkmcnt(6)
	s_nop 0
	v_mfma_scale_f32_32x32x64_f8f6f4 v[0:15], v[96:103], v[104:111], v[0:15], v162, v162 op_sel_hi:[0,0,0]
	v_max_f32_e32 v229, v64, v65
	v_max3_f32 v229, v229, v66, v67
	v_max3_f32 v229, v229, v68, v69
	v_max3_f32 v229, v229, v70, v71
	v_max3_f32 v229, v229, v72, v73
	v_max3_f32 v229, v229, v74, v75
	v_max3_f32 v229, v229, v76, v77
	v_max3_f32 v229, v229, v78, v79
	s_waitcnt lgkmcnt(4)
	v_mfma_scale_f32_32x32x64_f8f6f4 v[48:63], v[96:103], v[112:119], v[48:63], v162, v162 op_sel_hi:[0,0,0]
	v_max3_f32 v229, v229, v80, v81
	v_max3_f32 v229, v229, v82, v83
	v_max3_f32 v229, v229, v84, v85
	v_max3_f32 v229, v229, v86, v87
	v_max3_f32 v229, v229, v88, v89
	v_max3_f32 v229, v229, v90, v91
	v_max3_f32 v229, v229, v92, v93
	v_max3_f32 v229, v229, v94, v95
	v_mov_b32_e32 v160, v229
	s_nop 1
	v_permlane32_swap_b32_e32 v229, v160
	v_max_f32_e32 v229, v229, v160
	v_cmp_ge_f32_e32 vcc, s69, v229
	s_cmp_eq_u64 vcc, exec
	v_mov_b32_e32 v228, 1.0
	s_cbranch_scc0 .Lslow_b0
	s_waitcnt lgkmcnt(2)
	v_mfma_scale_f32_32x32x64_f8f6f4 v[16:31], v[96:103], v[148:155], v[16:31], v162, v162 op_sel_hi:[0,0,0]
	v_exp_f32_e32 v64, v64
	v_exp_f32_e32 v65, v65
	v_exp_f32_e32 v66, v66
	v_exp_f32_e32 v67, v67
	v_exp_f32_e32 v68, v68
	v_exp_f32_e32 v69, v69
	s_waitcnt lgkmcnt(0)
	v_mfma_scale_f32_32x32x64_f8f6f4 v[32:47], v[96:103], v[214:221], v[32:47], v162, v162 op_sel_hi:[0,0,0]
	v_exp_f32_e32 v70, v70
	v_exp_f32_e32 v71, v71
	v_exp_f32_e32 v72, v72
	v_exp_f32_e32 v73, v73
	v_exp_f32_e32 v74, v74
	v_exp_f32_e32 v75, v75
	v_mfma_scale_f32_16x16x128_f8f6f4 v[144:147], v[232:239], v[96:103], 0, v162, v162 op_sel_hi:[0,0,0]
	v_exp_f32_e32 v76, v76
	v_exp_f32_e32 v77, v77
	v_exp_f32_e32 v78, v78
	v_exp_f32_e32 v79, v79
	s_waitcnt vmcnt(0)
	s_barrier
.Ljoin_b0:
	ds_read_b128 v[104:107], v173 offset:27648
	ds_read_b64 v[108:109], v176 offset:27648
	ds_read_b128 v[110:113], v173 offset:28160
	ds_read_b64 v[114:115], v176 offset:27904
	ds_read_b128 v[148:151], v173 offset:29696
	ds_read_b64 v[152:153], v176 offset:28672
	ds_read_b128 v[154:157], v173 offset:30208
	ds_read_b64 v[158:159], v176 offset:28928
	ds_read_b128 v[214:217], v173 offset:33792
	ds_read_b64 v[218:219], v176 offset:31744
	ds_read_b128 v[220:223], v173 offset:34304
	ds_read_b64 v[224:225], v176 offset:32000
	v_fma_f32 v180, v226, v180, v144
	s_add_i32 s53, s53, 2
	v_mov_b32_e32 v179, v228

; template <bool FUSE>
; DEVINL void qkt(f32x16& p0, f32x16& p1, const char* Ks, const i32x8* q8, int r32, int hi, f32x16& e1) {
;   p0 = f32x16{}; p1 = f32x16{};
;   const char* ka = Ks + hi * 1024 + r32 * 16; const char* kb = Ks + 4096 + hi * 512 + r32 * 8;
;   const char* ra = Ks + 6144 + hi * 1024 + r32 * 16; const char* rb = Ks + 6144 + 2048 + hi * 512 + r32 * 8;
;   u32x4 fa[3][2]; u32x2 fb[3][2];
;     ...
;   QK_LD(0, 0);
; #pragma unroll
;   for (int t = 0; t < 3; ++t) {
;     if (t + 1 < 3) QK_LD(t + 1, (t + 1) % 3);
;     const i32x8 a0 = mk6((int)fa[t][0][0], (int)fa[t][0][1], (int)fa[t][0][2], (int)fa[t][0][3], (int)fb[t][0][0], (int)fb[t][0][1]);
;     const i32x8 a1 = mk6((int)fa[t][1][0], (int)fa[t][1][1], (int)fa[t][1][2], (int)fa[t][1][3], (int)fb[t][1][0], (int)fb[t][1][1]);
;     p0 = MFMA6(a0, q8[t], p0);
;     if (FUSE) {
; #pragma unroll
;       for (int r = 0; r < 3; ++r) { const int rr = t * 6 + r; if (rr < 16) e1[rr] = __builtin_amdgcn_exp2f(e1[rr]); }
;     }
;     p1 = MFMA6(a1, q8[t], p1);
;     if (FUSE) {
; #pragma unroll
;       for (int r = 3; r < 6; ++r) { const int rr = t * 6 + r; if (rr < 16) e1[rr] = __builtin_amdgcn_exp2f(e1[rr]); }
;     }
;     SBAR();
;   }
; DEVINL void pv_psm(f32x16* o, const VFrag& f, const i32x8& pa, f32x16& lsum, const i32x8& ones8,
;                    f32x16& p0, f32x16& p1, float& m_reg, float& mn, float& alpha, int kvalid, int hi) {
;   constexpr float C = MLA_SCALE * 1.4426950408889634f;
;     ...
;   if (kvalid < 64) {
; #pragma unroll
;     for (int r = 0; r < 16; ++r) { if (crow(r, hi) >= kvalid) p0[r] = -1e30f; if (32 + crow(r, hi) >= kvalid) p1[r] = -1e30f; }
;   }
;   PVM(0);
;   float pmax = p0[0];
; #pragma unroll
;   for (int r = 1; r < 16; ++r) pmax = fmaxf(pmax, p0[r]);
;   SBAR();
;   PVM(1);
; #pragma unroll
;   for (int r = 0; r < 16; ++r) pmax = fmaxf(pmax, p1[r]);
;   { auto rr = __builtin_amdgcn_permlane32_swap(__float_as_uint(pmax), __float_as_uint(pmax), false, false);
;     pmax = fmaxf(__uint_as_float(rr[0]), __uint_as_float(rr[1])); }
;   SBAR();
;   PVM(2);
;   if (__builtin_expect(__all(pmax - m_reg <= THR / MLA_SCALE), 1)) { mn = m_reg; alpha = 1.f; }
;   else { mn = fmaxf(m_reg, pmax); alpha = __builtin_amdgcn_exp2f((m_reg - mn) * C); m_reg = mn; }
;   const float mnC = PSHIFT - mn * C;
;   const f32x2 C2 = {C, C}, M2 = {mnC, mnC};
; #pragma unroll
.Lu1_dma_done:
	v_exp_f32_e32 v80, v80
	v_exp_f32_e32 v81, v81
	s_waitcnt lgkmcnt(10)
	v_mfma_scale_f32_32x32x64_f8f6f4 v[182:197], v[104:109], v[120:125], v[240:255], v162, v143 op_sel_hi:[0,0,0] cbsz:2 blgp:2
	v_exp_f32_e32 v82, v82
	v_exp_f32_e32 v83, v83
	v_exp_f32_e32 v84, v84
	v_exp_f32_e32 v85, v85
	s_waitcnt lgkmcnt(8)
	v_mfma_scale_f32_32x32x64_f8f6f4 v[198:213], v[110:115], v[120:125], v[240:255], v162, v143 op_sel_hi:[0,0,0] cbsz:2 blgp:2
	ds_read_b128 v[104:107], v140 offset:20480
	ds_read_b128 v[108:111], v140 offset:20992
	ds_read_b128 v[112:115], v140 offset:22528
	ds_read_b128 v[116:119], v140 offset:23040
	s_waitcnt lgkmcnt(10)
	v_exp_f32_e32 v86, v86
	v_mfma_scale_f32_32x32x64_f8f6f4 v[182:197], v[148:153], v[126:131], v[182:197], v162, v143 op_sel_hi:[0,0,0] cbsz:2 blgp:2
	v_exp_f32_e32 v87, v87
	v_exp_f32_e32 v88, v88
	v_exp_f32_e32 v89, v89
	v_exp_f32_e32 v90, v90
	s_waitcnt lgkmcnt(8)
	v_mfma_scale_f32_32x32x64_f8f6f4 v[198:213], v[154:159], v[126:131], v[198:213], v162, v143 op_sel_hi:[0,0,0] cbsz:2 blgp:2
	ds_read_b128 v[148:151], v140 offset:24576
	ds_read_b128 v[152:155], v140 offset:25088
	v_exp_f32_e32 v91, v91
	s_waitcnt lgkmcnt(8)
	v_exp_f32_e32 v92, v92
	v_mfma_scale_f32_32x32x64_f8f6f4 v[182:197], v[214:219], v[132:137], v[182:197], v162, v143 op_sel_hi:[0,0,0] cbsz:2 blgp:2
	v_exp_f32_e32 v93, v93
	v_exp_f32_e32 v94, v94
	v_exp_f32_e32 v95, v95
	v_cvt_pk_fp8_f32 v96, v64, v65
	v_cvt_pk_fp8_f32 v97, v68, v69
	s_waitcnt lgkmcnt(6)
	v_mfma_scale_f32_32x32x64_f8f6f4 v[198:213], v[220:225], v[132:137], v[198:213], v162, v143 op_sel_hi:[0,0,0] cbsz:2 blgp:2
	ds_read_b128 v[214:217], v140 offset:26624
	ds_read_b128 v[218:221], v140 offset:27136
	v_cvt_pk_fp8_f32 v98, v72, v73
	v_cvt_pk_fp8_f32 v99, v76, v77
	v_cvt_pk_fp8_f32 v96, v66, v67 op_sel:[0,0,1]
	v_cvt_pk_fp8_f32 v97, v70, v71 op_sel:[0,0,1]
	v_cvt_pk_fp8_f32 v98, v74, v75 op_sel:[0,0,1]
	v_cvt_pk_fp8_f32 v99, v78, v79 op_sel:[0,0,1]
	v_cvt_pk_fp8_f32 v100, v80, v81
	v_cvt_pk_fp8_f32 v101, v84, v85
	v_cvt_pk_fp8_f32 v102, v88, v89
	v_cvt_pk_fp8_f32 v103, v92, v93
	v_cvt_pk_fp8_f32 v100, v82, v83 op_sel:[0,0,1]
	v_cvt_pk_fp8_f32 v101, v86, v87 op_sel:[0,0,1]
	v_cvt_pk_fp8_f32 v102, v90, v91 op_sel:[0,0,1]
	v_cvt_pk_fp8_f32 v103, v94, v95 op_sel:[0,0,1]
	s_waitcnt lgkmcnt(6)
	s_nop 0
	v_mfma_scale_f32_32x32x64_f8f6f4 v[0:15], v[96:103], v[104:111], v[0:15], v162, v162 op_sel_hi:[0,0,0]
	v_max_f32_e32 v229, v182, v183
	v_max3_f32 v229, v229, v184, v185
	v_max3_f32 v229, v229, v186, v187
	v_max3_f32 v229, v229, v188, v189
	v_max3_f32 v229, v229, v190, v191
	v_max3_f32 v229, v229, v192, v193
	v_max3_f32 v229, v229, v194, v195
	v_max3_f32 v229, v229, v196, v197
	s_waitcnt lgkmcnt(4)
	v_mfma_scale_f32_32x32x64_f8f6f4 v[48:63], v[96:103], v[112:119], v[48:63], v162, v162 op_sel_hi:[0,0,0]
	v_max3_f32 v229, v229, v198, v199
	v_max3_f32 v229, v229, v200, v201
	v_max3_f32 v229, v229, v202, v203
	v_max3_f32 v229, v229, v204, v205
	v_max3_f32 v229, v229, v206, v207
	v_max3_f32 v229, v229, v208, v209
	v_max3_f32 v229, v229, v210, v211
	v_max3_f32 v229, v229, v212, v213
	v_mov_b32_e32 v160, v229
	s_nop 1
	v_permlane32_swap_b32_e32 v229, v160
	v_max_f32_e32 v229, v229, v160
	v_cmp_ge_f32_e32 vcc, s69, v229
	s_cmp_eq_u64 vcc, exec
	v_mov_b32_e32 v226, 1.0
	s_cbranch_scc0 .Lslow_a1
	s_waitcnt lgkmcnt(2)
	v_mfma_scale_f32_32x32x64_f8f6f4 v[16:31], v[96:103], v[148:155], v[16:31], v162, v162 op_sel_hi:[0,0,0]
	v_exp_f32_e32 v182, v182
	v_exp_f32_e32 v183, v183
	v_exp_f32_e32 v184, v184
	v_exp_f32_e32 v185, v185
	v_exp_f32_e32 v186, v186
	v_exp_f32_e32 v187, v187
	s_waitcnt lgkmcnt(0)
	v_mfma_scale_f32_32x32x64_f8f6f4 v[32:47], v[96:103], v[214:221], v[32:47], v162, v162 op_sel_hi:[0,0,0]
	v_exp_f32_e32 v188, v188
	v_exp_f32_e32 v189, v189
	v_exp_f32_e32 v190, v190
	v_exp_f32_e32 v191, v191
	v_exp_f32_e32 v192, v192
	v_exp_f32_e32 v193, v193
	v_mfma_scale_f32_16x16x128_f8f6f4 v[144:147], v[232:239], v[96:103], 0, v162, v162 op_sel_hi:[0,0,0]
	v_exp_f32_e32 v194, v194
	v_exp_f32_e32 v195, v195
	v_exp_f32_e32 v196, v196
	v_exp_f32_e32 v197, v197
.Ljoin_a1:
	ds_read_b128 v[104:107], v173 offset:0
	ds_read_b64 v[108:109], v176 offset:0
	ds_read_b128 v[110:113], v173 offset:512
	ds_read_b64 v[114:115], v176 offset:256
	ds_read_b128 v[148:151], v173 offset:2048
	ds_read_b64 v[152:153], v176 offset:1024
	ds_read_b128 v[154:157], v173 offset:2560
	ds_read_b64 v[158:159], v176 offset:1280
	ds_read_b128 v[214:217], v173 offset:6144
	ds_read_b64 v[218:219], v176 offset:4096
	ds_read_b128 v[220:223], v173 offset:6656
	ds_read_b64 v[224:225], v176 offset:4352
	v_fma_f32 v180, v179, v180, v144
	v_exp_f32_e32 v198, v198
	v_exp_f32_e32 v199, v199
	s_waitcnt lgkmcnt(10)
	v_mfma_scale_f32_32x32x64_f8f6f4 v[64:79], v[104:109], v[120:125], v[240:255], v162, v143 op_sel_hi:[0,0,0] cbsz:2 blgp:2
	v_exp_f32_e32 v200, v200
	v_exp_f32_e32 v201, v201
	v_exp_f32_e32 v202, v202
	v_exp_f32_e32 v203, v203
	s_waitcnt lgkmcnt(8)
	v_mfma_scale_f32_32x32x64_f8f6f4 v[80:95], v[110:115], v[120:125], v[240:255], v162, v143 op_sel_hi:[0,0,0] cbsz:2 blgp:2
	ds_read_b128 v[104:107], v140 offset:28672
	ds_read_b128 v[108:111], v140 offset:29184
	ds_read_b128 v[112:115], v140 offset:30720
	ds_read_b128 v[116:119], v140 offset:31232
	s_waitcnt lgkmcnt(10)
	v_exp_f32_e32 v204, v204
	v_mfma_scale_f32_32x32x64_f8f6f4 v[64:79], v[148:153], v[126:131], v[64:79], v162, v143 op_sel_hi:[0,0,0] cbsz:2 blgp:2
	v_exp_f32_e32 v205, v205
	v_exp_f32_e32 v206, v206
	v_exp_f32_e32 v207, v207
	v_exp_f32_e32 v208, v208
	s_waitcnt lgkmcnt(8)
; #define SBAR() __builtin_amdgcn_sched_barrier(0)
; #define TILE_SYNC() do { asm volatile("s_waitcnt vmcnt(0)" ::: "memory"); __syncthreads(); } while (0)
; #define RESC(a) do { if (__any((a) < 1.f)) { if (hi == 0) al_l[r32] = (a); asm volatile("s_waitcnt lgkmcnt(0)" ::: "memory"); \
;     for (int d = 0; d < 4; ++d) for (int r = 0; r < 16; ++r) o[d][r] *= al_l[crow(r, hi)]; } } while (0)
; #define LUPD(al) do { l_reg = l_reg * (al) + lsum[0]; } while (0)
; DEVINL void pv_psm(f32x16* o, const VFrag& f, const i32x8& pa, f32x16& lsum, const i32x8& ones8,
;                    f32x16& p0, f32x16& p1, float& m_reg, float& mn, float& alpha, int kvalid, int hi) {
;     ...
;   if (__builtin_expect(__all(pmax - m_reg <= THR / MLA_SCALE), 1)) { mn = m_reg; alpha = 1.f; }
;   else { mn = fmaxf(m_reg, pmax); alpha = __builtin_amdgcn_exp2f((m_reg - mn) * C); m_reg = mn; }
; DEVINL void mla_block(const Params& p, const bf16_t* __restrict__ Qn, const bf16_t* __restrict__ Qr, const char* __restrict__ K8, const char* __restrict__ Kp8,
;                       const char* __restrict__ V8, const bf16_t* __restrict__ Gb, bf16_t* __restrict__ Yb, char* lds, int pos0) {
;     ...
;     qkt<true>(pA0, pA1, KS(j + 1), q8, r32, hi, pB1);
;     pv_load(vf, VS(j), r32, hi); SBAR();
;     finishSM<true>(pB0, pB1, alB, l_reg, pa); SBAR();
;     { const float alPrev = alB; pv_psm(o, vf, pa, lsum, ones8, pA0, pA1, m_reg, mnA, alA, L - (j + 1) * KVBLK, hi); LUPD(alPrev); }
;     TILE_SYNC(); RESC(alA);
;   }
	v_mfma_scale_f32_32x32x64_f8f6f4 v[80:95], v[154:159], v[126:131], v[80:95], v162, v143 op_sel_hi:[0,0,0] cbsz:2 blgp:2
	ds_read_b128 v[148:151], v140 offset:32768
	ds_read_b128 v[152:155], v140 offset:33280
	v_exp_f32_e32 v209, v209
	s_waitcnt lgkmcnt(8)
	v_exp_f32_e32 v210, v210
	v_mfma_scale_f32_32x32x64_f8f6f4 v[64:79], v[214:219], v[132:137], v[64:79], v162, v143 op_sel_hi:[0,0,0] cbsz:2 blgp:2
	v_exp_f32_e32 v211, v211
	v_exp_f32_e32 v212, v212
	v_exp_f32_e32 v213, v213
	v_cvt_pk_fp8_f32 v96, v182, v183
	v_cvt_pk_fp8_f32 v97, v186, v187
	s_waitcnt lgkmcnt(6)
	v_mfma_scale_f32_32x32x64_f8f6f4 v[80:95], v[220:225], v[132:137], v[80:95], v162, v143 op_sel_hi:[0,0,0] cbsz:2 blgp:2
	ds_read_b128 v[214:217], v140 offset:34816
	ds_read_b128 v[218:221], v140 offset:35328
	v_cvt_pk_fp8_f32 v98, v190, v191
	v_cvt_pk_fp8_f32 v99, v194, v195
	v_cvt_pk_fp8_f32 v96, v184, v185 op_sel:[0,0,1]
	v_cvt_pk_fp8_f32 v97, v188, v189 op_sel:[0,0,1]
	v_cvt_pk_fp8_f32 v98, v192, v193 op_sel:[0,0,1]
	v_cvt_pk_fp8_f32 v99, v196, v197 op_sel:[0,0,1]
	v_cvt_pk_fp8_f32 v100, v198, v199
	v_cvt_pk_fp8_f32 v101, v202, v203
	v_cvt_pk_fp8_f32 v102, v206, v207
	v_cvt_pk_fp8_f32 v103, v210, v211
	v_cvt_pk_fp8_f32 v100, v200, v201 op_sel:[0,0,1]
	v_cvt_pk_fp8_f32 v101, v204, v205 op_sel:[0,0,1]
	v_cvt_pk_fp8_f32 v102, v208, v209 op_sel:[0,0,1]
	v_cvt_pk_fp8_f32 v103, v212, v213 op_sel:[0,0,1]
	s_waitcnt lgkmcnt(6)
	s_nop 0
	v_mfma_scale_f32_32x32x64_f8f6f4 v[0:15], v[96:103], v[104:111], v[0:15], v162, v162 op_sel_hi:[0,0,0]
	s_cmpk_gt_u32 s53, 0x101
	s_cbranch_scc1 .Lmask_last
	.Lmask_ret:
	v_max_f32_e32 v229, v64, v65
	v_max3_f32 v229, v229, v66, v67
	v_max3_f32 v229, v229, v68, v69
	v_max3_f32 v229, v229, v70, v71
	v_max3_f32 v229, v229, v72, v73
	v_max3_f32 v229, v229, v74, v75
	v_max3_f32 v229, v229, v76, v77
	v_max3_f32 v229, v229, v78, v79
	s_waitcnt lgkmcnt(4)
	v_mfma_scale_f32_32x32x64_f8f6f4 v[48:63], v[96:103], v[112:119], v[48:63], v162, v162 op_sel_hi:[0,0,0]
	v_max3_f32 v229, v229, v80, v81
	v_max3_f32 v229, v229, v82, v83
	v_max3_f32 v229, v229, v84, v85
	v_max3_f32 v229, v229, v86, v87
	v_max3_f32 v229, v229, v88, v89
	v_max3_f32 v229, v229, v90, v91
	v_max3_f32 v229, v229, v92, v93
	v_max3_f32 v229, v229, v94, v95
	v_mov_b32_e32 v160, v229
	s_nop 1
	v_permlane32_swap_b32_e32 v229, v160
	v_max_f32_e32 v229, v229, v160
	v_cmp_ge_f32_e32 vcc, s69, v229
	s_cmp_eq_u64 vcc, exec
	v_mov_b32_e32 v228, 1.0
	s_cbranch_scc0 .Lslow_b1
	s_waitcnt lgkmcnt(2)
	v_mfma_scale_f32_32x32x64_f8f6f4 v[16:31], v[96:103], v[148:155], v[16:31], v162, v162 op_sel_hi:[0,0,0]
	v_exp_f32_e32 v64, v64
	v_exp_f32_e32 v65, v65
	v_exp_f32_e32 v66, v66
	v_exp_f32_e32 v67, v67
	v_exp_f32_e32 v68, v68
	v_exp_f32_e32 v69, v69
	s_waitcnt lgkmcnt(0)
	v_mfma_scale_f32_32x32x64_f8f6f4 v[32:47], v[96:103], v[214:221], v[32:47], v162, v162 op_sel_hi:[0,0,0]
	v_exp_f32_e32 v70, v70
	v_exp_f32_e32 v71, v71
	v_exp_f32_e32 v72, v72
	v_exp_f32_e32 v73, v73
	v_exp_f32_e32 v74, v74
	v_exp_f32_e32 v75, v75
	v_mfma_scale_f32_16x16x128_f8f6f4 v[144:147], v[232:239], v[96:103], 0, v162, v162 op_sel_hi:[0,0,0]
	v_exp_f32_e32 v76, v76
	v_exp_f32_e32 v77, v77
	v_exp_f32_e32 v78, v78
	v_exp_f32_e32 v79, v79
	s_waitcnt vmcnt(0)
	s_barrier
.Ljoin_b1:
	ds_read_b128 v[104:107], v173 offset:9216
	ds_read_b64 v[108:109], v176 offset:9216
	ds_read_b128 v[110:113], v173 offset:9728
	ds_read_b64 v[114:115], v176 offset:9472
	ds_read_b128 v[148:151], v173 offset:11264
	ds_read_b64 v[152:153], v176 offset:10240
	ds_read_b128 v[154:157], v173 offset:11776
	ds_read_b64 v[158:159], v176 offset:10496
	ds_read_b128 v[214:217], v173 offset:15360
	ds_read_b64 v[218:219], v176 offset:13312
	ds_read_b128 v[220:223], v173 offset:15872
	ds_read_b64 v[224:225], v176 offset:13568
	v_fma_f32 v180, v226, v180, v144
	s_add_i32 s53, s53, 2
	s_cmpk_gt_u32 s53, 0x102
	s_cbranch_scc1 .Lexit_glue
	v_mov_b32_e32 v179, v228
	s_branch .LBB0_560
.Lslow_a0:
	s_waitcnt lgkmcnt(2)
	v_mfma_scale_f32_32x32x64_f8f6f4 v[16:31], v[96:103], v[148:155], v[16:31], v162, v162 op_sel_hi:[0,0,0]
	s_waitcnt lgkmcnt(0)
	v_mfma_scale_f32_32x32x64_f8f6f4 v[32:47], v[96:103], v[214:221], v[32:47], v162, v162 op_sel_hi:[0,0,0]
	v_mfma_scale_f32_16x16x128_f8f6f4 v[144:147], v[232:239], v[96:103], 0, v162, v162 op_sel_hi:[0,0,0]
	v_sub_f32_e32 v141, v229, v164
	v_max_f32_e32 v141, 0, v141
	v_exp_f32_e64 v226, -v141
	v_sub_f32_e32 v230, v230, v141
	v_mov_b32_e32 v240, v230
	v_mov_b32_e32 v241, v230
	v_mov_b32_e32 v242, v230
	v_mov_b32_e32 v243, v230
	v_mov_b32_e32 v244, v230
	v_mov_b32_e32 v245, v230
	v_mov_b32_e32 v246, v230
	v_mov_b32_e32 v247, v230
	v_mov_b32_e32 v248, v230
	v_mov_b32_e32 v249, v230
	v_mov_b32_e32 v250, v230
	v_mov_b32_e32 v251, v230
	v_mov_b32_e32 v252, v230
	v_mov_b32_e32 v253, v230
	v_mov_b32_e32 v254, v230
	v_mov_b32_e32 v255, v230
	v_sub_f32_e32 v182, v182, v141
	v_sub_f32_e32 v183, v183, v141
	v_sub_f32_e32 v184, v184, v141
	v_sub_f32_e32 v185, v185, v141
	v_sub_f32_e32 v186, v186, v141
	v_sub_f32_e32 v187, v187, v141
	v_sub_f32_e32 v188, v188, v141
	v_sub_f32_e32 v189, v189, v141
	v_sub_f32_e32 v190, v190, v141
	v_sub_f32_e32 v191, v191, v141
	v_sub_f32_e32 v192, v192, v141
	v_sub_f32_e32 v193, v193, v141
	v_sub_f32_e32 v194, v194, v141
	v_sub_f32_e32 v195, v195, v141
	v_sub_f32_e32 v196, v196, v141
	v_sub_f32_e32 v197, v197, v141
	v_sub_f32_e32 v198, v198, v141
	v_sub_f32_e32 v199, v199, v141
	v_sub_f32_e32 v200, v200, v141
	v_sub_f32_e32 v201, v201, v141
	v_sub_f32_e32 v202, v202, v141
	v_sub_f32_e32 v203, v203, v141
	v_sub_f32_e32 v204, v204, v141
	v_sub_f32_e32 v205, v205, v141
	v_sub_f32_e32 v206, v206, v141
	v_sub_f32_e32 v207, v207, v141
	v_sub_f32_e32 v208, v208, v141
	v_sub_f32_e32 v209, v209, v141
	v_sub_f32_e32 v210, v210, v141
	v_sub_f32_e32 v211, v211, v141
	v_sub_f32_e32 v212, v212, v141
	v_sub_f32_e32 v213, v213, v141
	s_and_saveexec_b64 s[16:17], s[6:7]
	ds_write_b32 v178, v226 offset:128
	s_or_b64 exec, exec, s[16:17]
	s_waitcnt lgkmcnt(0)
; DEVINL void pv_psm(f32x16* o, const VFrag& f, const i32x8& pa, f32x16& lsum, const i32x8& ones8,
;                    f32x16& p0, f32x16& p1, float& m_reg, float& mn, float& alpha, int kvalid, int hi) {
;     ...
;   if (__builtin_expect(__all(pmax - m_reg <= THR / MLA_SCALE), 1)) { mn = m_reg; alpha = 1.f; }
;   else { mn = fmaxf(m_reg, pmax); alpha = __builtin_amdgcn_exp2f((m_reg - mn) * C); m_reg = mn; }
	v_add_u32_e32 v142, v171, v177
	ds_read_b128 v[104:107], v142 offset:224
	ds_read_b128 v[108:111], v142 offset:192
	ds_read_b128 v[112:115], v142 offset:160
	ds_read_b128 v[116:119], v142 offset:128
	s_waitcnt lgkmcnt(0)
	v_pk_mul_f32 v[12:13], v[12:13], v[104:105]
	v_pk_mul_f32 v[8:9], v[8:9], v[108:109]
	v_pk_mul_f32 v[4:5], v[4:5], v[112:113]
	v_pk_mul_f32 v[14:15], v[14:15], v[106:107]
	v_pk_mul_f32 v[10:11], v[10:11], v[110:111]
	v_pk_mul_f32 v[6:7], v[6:7], v[114:115]
	v_pk_mul_f32 v[2:3], v[2:3], v[118:119]
	v_pk_mul_f32 v[0:1], v[0:1], v[116:117]
	v_pk_mul_f32 v[60:61], v[60:61], v[104:105]
	v_pk_mul_f32 v[56:57], v[56:57], v[108:109]
	v_pk_mul_f32 v[52:53], v[52:53], v[112:113]
	v_pk_mul_f32 v[62:63], v[62:63], v[106:107]
	v_pk_mul_f32 v[58:59], v[58:59], v[110:111]
	v_pk_mul_f32 v[54:55], v[54:55], v[114:115]
	v_pk_mul_f32 v[50:51], v[50:51], v[118:119]
	v_pk_mul_f32 v[48:49], v[48:49], v[116:117]
	v_pk_mul_f32 v[28:29], v[28:29], v[104:105]
	v_pk_mul_f32 v[24:25], v[24:25], v[108:109]
	v_pk_mul_f32 v[20:21], v[20:21], v[112:113]
	v_pk_mul_f32 v[30:31], v[30:31], v[106:107]
	v_pk_mul_f32 v[26:27], v[26:27], v[110:111]
	v_pk_mul_f32 v[22:23], v[22:23], v[114:115]
	v_pk_mul_f32 v[18:19], v[18:19], v[118:119]
	v_pk_mul_f32 v[16:17], v[16:17], v[116:117]
	v_pk_mul_f32 v[44:45], v[44:45], v[104:105]
	v_pk_mul_f32 v[40:41], v[40:41], v[108:109]
	v_pk_mul_f32 v[36:37], v[36:37], v[112:113]
	v_pk_mul_f32 v[46:47], v[46:47], v[106:107]
	v_pk_mul_f32 v[42:43], v[42:43], v[110:111]
	v_pk_mul_f32 v[38:39], v[38:39], v[114:115]
	v_pk_mul_f32 v[34:35], v[34:35], v[118:119]
	v_pk_mul_f32 v[32:33], v[32:33], v[116:117]
	v_exp_f32_e32 v182, v182
	v_exp_f32_e32 v183, v183
	v_exp_f32_e32 v184, v184
	v_exp_f32_e32 v185, v185
	v_exp_f32_e32 v186, v186
	v_exp_f32_e32 v187, v187
	v_exp_f32_e32 v188, v188
	v_exp_f32_e32 v189, v189
	v_exp_f32_e32 v190, v190
	v_exp_f32_e32 v191, v191
	v_exp_f32_e32 v192, v192
	v_exp_f32_e32 v193, v193
	v_exp_f32_e32 v194, v194
	v_exp_f32_e32 v195, v195
	v_exp_f32_e32 v196, v196
	v_exp_f32_e32 v197, v197
	s_branch .Ljoin_a0
.Lslow_b0:
	s_waitcnt lgkmcnt(2)
	v_mfma_scale_f32_32x32x64_f8f6f4 v[16:31], v[96:103], v[148:155], v[16:31], v162, v162 op_sel_hi:[0,0,0]
	s_waitcnt lgkmcnt(0)
	v_mfma_scale_f32_32x32x64_f8f6f4 v[32:47], v[96:103], v[214:221], v[32:47], v162, v162 op_sel_hi:[0,0,0]
	v_mfma_scale_f32_16x16x128_f8f6f4 v[144:147], v[232:239], v[96:103], 0, v162, v162 op_sel_hi:[0,0,0]
	s_waitcnt vmcnt(0)
	s_barrier
	v_sub_f32_e32 v141, v229, v164
	v_max_f32_e32 v141, 0, v141
	v_exp_f32_e64 v228, -v141
	v_sub_f32_e32 v230, v230, v141
	v_mov_b32_e32 v240, v230
	v_mov_b32_e32 v241, v230
	v_mov_b32_e32 v242, v230
	v_mov_b32_e32 v243, v230
	v_mov_b32_e32 v244, v230
	v_mov_b32_e32 v245, v230
	v_mov_b32_e32 v246, v230
	v_mov_b32_e32 v247, v230
	v_mov_b32_e32 v248, v230
	v_mov_b32_e32 v249, v230
	v_mov_b32_e32 v250, v230
	v_mov_b32_e32 v251, v230
	v_mov_b32_e32 v252, v230
	v_mov_b32_e32 v253, v230
	v_mov_b32_e32 v254, v230
	v_mov_b32_e32 v255, v230
	v_sub_f32_e32 v64, v64, v141
	v_sub_f32_e32 v65, v65, v141
	v_sub_f32_e32 v66, v66, v141
	v_sub_f32_e32 v67, v67, v141
	v_sub_f32_e32 v68, v68, v141
	v_sub_f32_e32 v69, v69, v141
	v_sub_f32_e32 v70, v70, v141
	v_sub_f32_e32 v71, v71, v141
	v_sub_f32_e32 v72, v72, v141
	v_sub_f32_e32 v73, v73, v141
	v_sub_f32_e32 v74, v74, v141
	v_sub_f32_e32 v75, v75, v141
	v_sub_f32_e32 v76, v76, v141
	v_sub_f32_e32 v77, v77, v141
	v_sub_f32_e32 v78, v78, v141
	v_sub_f32_e32 v79, v79, v141
	v_sub_f32_e32 v80, v80, v141
	v_sub_f32_e32 v81, v81, v141
	v_sub_f32_e32 v82, v82, v141
	v_sub_f32_e32 v83, v83, v141
	v_sub_f32_e32 v84, v84, v141
	v_sub_f32_e32 v85, v85, v141
	v_sub_f32_e32 v86, v86, v141
	v_sub_f32_e32 v87, v87, v141
	v_sub_f32_e32 v88, v88, v141
	v_sub_f32_e32 v89, v89, v141
	v_sub_f32_e32 v90, v90, v141
	v_sub_f32_e32 v91, v91, v141
	v_sub_f32_e32 v92, v92, v141
	v_sub_f32_e32 v93, v93, v141
	v_sub_f32_e32 v94, v94, v141
	v_sub_f32_e32 v95, v95, v141
	s_and_saveexec_b64 s[16:17], s[6:7]
	ds_write_b32 v178, v228 offset:128
	s_or_b64 exec, exec, s[16:17]
	s_waitcnt lgkmcnt(0)
	v_add_u32_e32 v142, v171, v177
	ds_read_b128 v[104:107], v142 offset:224
	ds_read_b128 v[108:111], v142 offset:192
	ds_read_b128 v[112:115], v142 offset:160
	ds_read_b128 v[116:119], v142 offset:128
	s_waitcnt lgkmcnt(0)
	v_pk_mul_f32 v[12:13], v[12:13], v[104:105]
	v_pk_mul_f32 v[8:9], v[8:9], v[108:109]
	v_pk_mul_f32 v[4:5], v[4:5], v[112:113]
	v_pk_mul_f32 v[14:15], v[14:15], v[106:107]
	v_pk_mul_f32 v[10:11], v[10:11], v[110:111]
	v_pk_mul_f32 v[6:7], v[6:7], v[114:115]
	v_pk_mul_f32 v[2:3], v[2:3], v[118:119]
	v_pk_mul_f32 v[0:1], v[0:1], v[116:117]
	v_pk_mul_f32 v[60:61], v[60:61], v[104:105]
	v_pk_mul_f32 v[56:57], v[56:57], v[108:109]
	v_pk_mul_f32 v[52:53], v[52:53], v[112:113]
	v_pk_mul_f32 v[62:63], v[62:63], v[106:107]
	v_pk_mul_f32 v[58:59], v[58:59], v[110:111]
	v_pk_mul_f32 v[54:55], v[54:55], v[114:115]
	v_pk_mul_f32 v[50:51], v[50:51], v[118:119]
	v_pk_mul_f32 v[48:49], v[48:49], v[116:117]
	v_pk_mul_f32 v[28:29], v[28:29], v[104:105]
	v_pk_mul_f32 v[24:25], v[24:25], v[108:109]
	v_pk_mul_f32 v[20:21], v[20:21], v[112:113]
	v_pk_mul_f32 v[30:31], v[30:31], v[106:107]
	v_pk_mul_f32 v[26:27], v[26:27], v[110:111]
	v_pk_mul_f32 v[22:23], v[22:23], v[114:115]
	v_pk_mul_f32 v[18:19], v[18:19], v[118:119]
	v_pk_mul_f32 v[16:17], v[16:17], v[116:117]
	v_pk_mul_f32 v[44:45], v[44:45], v[104:105]
	v_pk_mul_f32 v[40:41], v[40:41], v[108:109]
	v_pk_mul_f32 v[36:37], v[36:37], v[112:113]
	v_pk_mul_f32 v[46:47], v[46:47], v[106:107]
	v_pk_mul_f32 v[42:43], v[42:43], v[110:111]
	v_pk_mul_f32 v[38:39], v[38:39], v[114:115]
	v_pk_mul_f32 v[34:35], v[34:35], v[118:119]
	v_pk_mul_f32 v[32:33], v[32:33], v[116:117]
	v_exp_f32_e32 v64, v64
	v_exp_f32_e32 v65, v65
	v_exp_f32_e32 v66, v66
	v_exp_f32_e32 v67, v67
	v_exp_f32_e32 v68, v68
	v_exp_f32_e32 v69, v69
	v_exp_f32_e32 v70, v70
	v_exp_f32_e32 v71, v71
	v_exp_f32_e32 v72, v72
	v_exp_f32_e32 v73, v73
	v_exp_f32_e32 v74, v74
	v_exp_f32_e32 v75, v75
	v_exp_f32_e32 v76, v76
	v_exp_f32_e32 v77, v77
	v_exp_f32_e32 v78, v78
	v_exp_f32_e32 v79, v79
	s_branch .Ljoin_b0

; DEVINL int crow(int r, int hi) { return (r & 3) + 8 * (r >> 2) + 4 * hi; }
; #define SBAR() __builtin_amdgcn_sched_barrier(0)
; #define LSUM() do { lsum = MFMA8(ones8, pa, (f32x16{})); } while (0)
; #define LUPD(al) do { l_reg = l_reg * (al) + lsum[0]; } while (0)
; DEVINL void partialSM(f32x16& p0, f32x16& p1, float& m_reg, float& mn, float& alpha, int kvalid, int hi) {
;     ...
;   if (kvalid < 64) {
; #pragma unroll
;     for (int r = 0; r < 16; ++r) { if (crow(r, hi) >= kvalid) p0[r] = -1e30f; if (32 + crow(r, hi) >= kvalid) p1[r] = -1e30f; }
;   }
; DEVINL void mla_block(const Params& p, const bf16_t* __restrict__ Qn, const bf16_t* __restrict__ Qr, const char* __restrict__ K8, const char* __restrict__ Kp8,
;                       const char* __restrict__ V8, const bf16_t* __restrict__ Gb, bf16_t* __restrict__ Yb, char* lds, int pos0) {
;     ...
;   pv_load(vf, VS(NT - 1), r32, hi); SBAR();
;   finishSM<false>(pA0, pA1, alA, l_reg, pa); SBAR();
;   pv_mma(o, vf, pa); LSUM(); LUPD(alA);
;   if (hi == 0) li_l[r32] = l_reg; asm volatile("s_waitcnt lgkmcnt(0)" ::: "memory");
.Lmask_last:
	v_mov_b32_e32 v72, v163
	v_mov_b32_e32 v73, v163
	v_mov_b32_e32 v74, v163
	v_mov_b32_e32 v75, v163
	v_mov_b32_e32 v76, v163
	v_mov_b32_e32 v77, v163
	v_mov_b32_e32 v78, v163
	v_mov_b32_e32 v79, v163
	v_mov_b32_e32 v80, v163
	v_mov_b32_e32 v81, v163
	v_mov_b32_e32 v82, v163
	v_mov_b32_e32 v83, v163
	v_mov_b32_e32 v84, v163
	v_mov_b32_e32 v85, v163
	v_mov_b32_e32 v86, v163
	v_mov_b32_e32 v87, v163
	v_mov_b32_e32 v88, v163
	v_mov_b32_e32 v89, v163
	v_mov_b32_e32 v90, v163
	v_mov_b32_e32 v91, v163
	v_mov_b32_e32 v92, v163
	v_mov_b32_e32 v93, v163
	v_mov_b32_e32 v94, v163
	v_mov_b32_e32 v95, v163
	s_branch .Lmask_ret
.Lexit_glue:
	s_waitcnt lgkmcnt(0)
	v_mov_b32_e32 v198, v228
	v_mov_b32_e32 v186, v79
	v_mov_b32_e32 v185, v78
	v_mov_b32_e32 v190, v77
	v_mov_b32_e32 v188, v76
	v_mov_b32_e32 v184, v75
	v_mov_b32_e32 v183, v74
	v_mov_b32_e32 v194, v73
	v_mov_b32_e32 v193, v72
	v_mov_b32_e32 v192, v71
	v_mov_b32_e32 v191, v70
	v_mov_b32_e32 v196, v69
	v_mov_b32_e32 v195, v68
	v_mov_b32_e32 v189, v67
	v_mov_b32_e32 v187, v66
	v_mov_b32_e32 v197, v65
	v_mov_b32_e32 v65, v64
	v_mov_b32_e32 v160, v80
	v_mov_b32_e32 v161, v81
	v_mov_b32_e32 v158, v82
	v_mov_b32_e32 v159, v83
	v_mov_b32_e32 v156, v86
	v_mov_b32_e32 v157, v87
	v_mov_b32_e32 v154, v88
	v_mov_b32_e32 v155, v89
	v_mov_b32_e32 v152, v90
	v_mov_b32_e32 v153, v91
	v_mov_b32_e32 v150, v92
	v_mov_b32_e32 v151, v93
	v_mov_b32_e32 v148, v94
	v_mov_b32_e32 v149, v95
	v_mov_b32_e32 v82, v84
	v_mov_b32_e32 v83, v85
.LBB0_578:
	s_setprio 0
	ds_read_b128 v[128:131], v173 offset:36864
	ds_read_b128 v[132:135], v173 offset:37376
	ds_read_b128 v[120:123], v173 offset:38912
	ds_read_b128 v[124:127], v173 offset:39424
	ds_read_b128 v[92:95], v173 offset:40960
	ds_read_b128 v[96:99], v173 offset:41472
	ds_read_b128 v[84:87], v173 offset:43008
	ds_read_b128 v[88:91], v173 offset:43520
	v_exp_f32_e32 v64, v160
	v_exp_f32_e32 v67, v161
	v_exp_f32_e32 v70, v82
	v_exp_f32_e32 v71, v83
	v_exp_f32_e32 v74, v154
	v_exp_f32_e32 v75, v155
	v_exp_f32_e32 v78, v150
	v_exp_f32_e32 v79, v151
	v_mov_b32_e32 v100, v139
	v_mov_b32_e32 v104, v139
	v_mov_b32_e32 v101, v139
	v_mov_b32_e32 v105, v139
	v_mov_b32_e32 v102, v139
	v_mov_b32_e32 v106, v139
	v_mov_b32_e32 v103, v139
	v_mov_b32_e32 v107, v139
	v_exp_f32_e32 v68, v158
	v_exp_f32_e32 v69, v159
	v_exp_f32_e32 v72, v156
	v_exp_f32_e32 v73, v157
	v_exp_f32_e32 v76, v152
	v_exp_f32_e32 v77, v153
	v_exp_f32_e32 v80, v148
	v_exp_f32_e32 v81, v149
	v_cvt_pk_fp8_f32 v100, v65, v197
	v_cvt_pk_fp8_f32 v104, v64, v67
	v_cvt_pk_fp8_f32 v101, v195, v196
	v_cvt_pk_fp8_f32 v105, v70, v71
	v_cvt_pk_fp8_f32 v102, v193, v194
	v_cvt_pk_fp8_f32 v106, v74, v75
	v_cvt_pk_fp8_f32 v103, v188, v190
	v_cvt_pk_fp8_f32 v107, v78, v79
	v_cvt_pk_fp8_f32 v100, v187, v189 op_sel:[0,0,1]
	v_cvt_pk_fp8_f32 v104, v68, v69 op_sel:[0,0,1]
	v_cvt_pk_fp8_f32 v101, v191, v192 op_sel:[0,0,1]
	v_cvt_pk_fp8_f32 v105, v72, v73 op_sel:[0,0,1]
	v_cvt_pk_fp8_f32 v102, v183, v184 op_sel:[0,0,1]
	v_cvt_pk_fp8_f32 v106, v76, v77 op_sel:[0,0,1]
	v_cvt_pk_fp8_f32 v103, v185, v186 op_sel:[0,0,1]
	v_cvt_pk_fp8_f32 v107, v80, v81 op_sel:[0,0,1]
	s_and_saveexec_b64 s[4:5], s[6:7]
	s_cbranch_execz .LBB0_549
	s_nop 1
	v_mfma_scale_f32_16x16x128_f8f6f4 v[68:71], v[232:239], v[100:107], 0, v162, v162 op_sel_hi:[0,0,0]
	s_nop 15
	s_nop 3
	v_fmac_f32_e32 v68, v198, v180
	ds_write_b32 v178, v68
	s_branch .LBB0_549
